# att2: no stagger sleep, task-head wait dropped (back-edge vmcnt(8) already covers q/ml), merge waits vmcnt(7)
# speedup vs baseline: 1.0348x; 1.0010x over previous
.LBB0_1117:
	s_andn2_b64 vcc, exec, s[46:47]
	s_waitcnt lgkmcnt(0)
	s_barrier
	s_cbranch_vccnz .LBB0_1119
	s_nop 0
.LBB0_1119:
	s_waitcnt vmcnt(0)
	v_or_b32_e32 v183, s38, v139
	s_mov_b32 s23, 0
	s_mov_b32 s20, s12

.LBB0_1124:
	ds_read_b128 v[44:47], v248
	ds_read_b128 v[48:51], v248 offset:1024
	ds_read_b128 v[52:55], v249
	ds_read_b128 v[60:63], v249 offset:1024
	ds_read_b128 v[56:59], v250
	ds_read_b128 v[64:67], v250 offset:1024
	ds_read_b128 v[68:71], v220
	ds_read_b128 v[72:75], v220 offset:1024
	v_or_b32_e32 v43, s28, v139
	s_andn2_b64 vcc, exec, s[36:37]
	s_cbranch_vccz .Latt2_wait_done
	s_waitcnt vmcnt(0)
.Latt2_wait_done:
	v_max3_f32 v42, v106, v110, v112
	s_waitcnt lgkmcnt(7)
	v_mfma_f32_16x16x32_bf16 v[44:47], v[44:47], v[38:41], 0
	v_cmp_gt_u32_e32 vcc, v138, v43
	s_waitcnt lgkmcnt(5)
	v_mfma_f32_16x16x32_bf16 v[44:47], v[52:55], v[34:37], v[44:47]
	v_mov_b32_e32 v52, s22
	s_waitcnt lgkmcnt(3)
	v_mfma_f32_16x16x32_bf16 v[44:47], v[56:59], v[28:31], v[44:47]
	v_mfma_f32_16x16x32_bf16 v[48:51], v[48:51], v[38:41], 0
	s_waitcnt lgkmcnt(1)
	v_mfma_f32_16x16x32_bf16 v[44:47], v[68:71], v[24:27], v[44:47]
	v_mfma_f32_16x16x32_bf16 v[48:51], v[60:63], v[34:37], v[48:51]
	v_mfma_f32_16x16x32_bf16 v[48:51], v[64:67], v[28:31], v[48:51]
	s_nop 5
	v_cndmask_b32_e32 v52, v44, v52, vcc
	v_cmp_lt_u32_e32 vcc, v138, v43
	s_nop 1
	v_cndmask_b32_e32 v58, v52, v44, vcc
	v_or_b32_e32 v44, 2, v138
	v_cndmask_b32_e32 v59, v217, v45, vcc
	v_cmp_le_u32_e32 vcc, v44, v43
	v_or_b32_e32 v44, 3, v138
	v_or_b32_e32 v45, 4, v138
	v_cndmask_b32_e32 v60, v217, v46, vcc
	v_cmp_le_u32_e32 vcc, v44, v43
	v_mov_b32_e32 v44, s22
	s_nop 0
	v_cndmask_b32_e32 v61, v217, v47, vcc
	s_waitcnt lgkmcnt(0)
	v_mfma_f32_16x16x32_bf16 v[46:49], v[72:75], v[24:27], v[48:51]
	v_cmp_gt_u32_e32 vcc, v45, v43
	s_nop 6
	v_cndmask_b32_e32 v62, v46, v44, vcc
	v_or_b32_e32 v44, 5, v138
	v_cmp_le_u32_e32 vcc, v44, v43
	v_or_b32_e32 v44, 6, v138
	s_nop 0
	v_cndmask_b32_e32 v63, v217, v47, vcc
	v_cmp_le_u32_e32 vcc, v44, v43
	v_or_b32_e32 v44, 7, v138
	s_nop 0
	v_cndmask_b32_e32 v64, v217, v48, vcc
	v_cmp_le_u32_e32 vcc, v44, v43
	s_nop 1
	v_cndmask_b32_e32 v65, v217, v49, vcc
	ds_read_b128 v[44:47], v248 offset:8192
	ds_read_b128 v[48:51], v248 offset:9216
	ds_read_b128 v[52:55], v249 offset:8192
	ds_read_b128 v[68:71], v249 offset:9216
	ds_read_b128 v[72:75], v250 offset:8192
	ds_read_b128 v[76:79], v250 offset:9216
	ds_read_b128 v[80:83], v220 offset:8192
	ds_read_b128 v[84:87], v220 offset:9216
	s_waitcnt lgkmcnt(7)
	v_mfma_f32_16x16x32_bf16 v[44:47], v[44:47], v[38:41], 0
	s_waitcnt lgkmcnt(5)
	v_mfma_f32_16x16x32_bf16 v[44:47], v[52:55], v[34:37], v[44:47]
	v_or_b32_e32 v53, 32, v138
	v_mov_b32_e32 v52, s22
	v_cmp_gt_u32_e32 vcc, v53, v43
	s_waitcnt lgkmcnt(3)
	v_mfma_f32_16x16x32_bf16 v[44:47], v[72:75], v[28:31], v[44:47]
	v_mfma_f32_16x16x32_bf16 v[48:51], v[48:51], v[38:41], 0
	s_waitcnt lgkmcnt(1)
	v_mfma_f32_16x16x32_bf16 v[44:47], v[80:83], v[24:27], v[44:47]
	v_mfma_f32_16x16x32_bf16 v[48:51], v[68:71], v[34:37], v[48:51]
	v_mfma_f32_16x16x32_bf16 v[48:51], v[76:79], v[28:31], v[48:51]
	s_nop 5
	v_cndmask_b32_e32 v66, v44, v52, vcc
	v_or_b32_e32 v44, 33, v138
	v_cmp_le_u32_e32 vcc, v44, v43
	v_or_b32_e32 v44, 34, v138
	s_nop 0
	v_cndmask_b32_e32 v67, v217, v45, vcc
	v_cmp_le_u32_e32 vcc, v44, v43
	v_or_b32_e32 v44, 35, v138
	v_or_b32_e32 v45, 36, v138
	v_cndmask_b32_e32 v68, v217, v46, vcc
	v_cmp_le_u32_e32 vcc, v44, v43
	v_mov_b32_e32 v44, s22
	s_nop 0
	v_cndmask_b32_e32 v69, v217, v47, vcc
	s_waitcnt lgkmcnt(0)
	v_mfma_f32_16x16x32_bf16 v[46:49], v[84:87], v[24:27], v[48:51]
	v_cmp_gt_u32_e32 vcc, v45, v43
	s_nop 6
	v_cndmask_b32_e32 v70, v46, v44, vcc
	v_or_b32_e32 v44, 37, v138
	v_cmp_le_u32_e32 vcc, v44, v43
	v_or_b32_e32 v44, 38, v138
	s_nop 0
	v_cndmask_b32_e32 v71, v217, v47, vcc
	v_cmp_le_u32_e32 vcc, v44, v43
	v_or_b32_e32 v44, 39, v138
	s_nop 0
	v_cndmask_b32_e32 v72, v217, v48, vcc
	v_cmp_le_u32_e32 vcc, v44, v43
	s_nop 1
	v_cndmask_b32_e32 v73, v217, v49, vcc
	ds_read_b128 v[44:47], v248 offset:16384
	ds_read_b128 v[48:51], v248 offset:17408
	ds_read_b128 v[52:55], v249 offset:16384
	ds_read_b128 v[76:79], v249 offset:17408
	ds_read_b128 v[80:83], v250 offset:16384
	ds_read_b128 v[84:87], v250 offset:17408
	ds_read_b128 v[88:91], v220 offset:16384
	ds_read_b128 v[92:95], v220 offset:17408
	s_waitcnt lgkmcnt(7)
	v_mfma_f32_16x16x32_bf16 v[44:47], v[44:47], v[38:41], 0
	s_waitcnt lgkmcnt(5)
	v_mfma_f32_16x16x32_bf16 v[44:47], v[52:55], v[34:37], v[44:47]
	v_or_b32_e32 v53, 64, v138
	v_mov_b32_e32 v52, s22
	v_cmp_gt_u32_e32 vcc, v53, v43
	s_waitcnt lgkmcnt(3)
	v_mfma_f32_16x16x32_bf16 v[44:47], v[80:83], v[28:31], v[44:47]
	v_mfma_f32_16x16x32_bf16 v[48:51], v[48:51], v[38:41], 0
	s_waitcnt lgkmcnt(1)
	v_mfma_f32_16x16x32_bf16 v[44:47], v[88:91], v[24:27], v[44:47]
	v_mfma_f32_16x16x32_bf16 v[48:51], v[76:79], v[34:37], v[48:51]
	v_mfma_f32_16x16x32_bf16 v[48:51], v[84:87], v[28:31], v[48:51]
	s_nop 5
	v_cndmask_b32_e32 v74, v44, v52, vcc
	v_or_b32_e32 v44, 0x41, v138
	v_cmp_le_u32_e32 vcc, v44, v43
	v_or_b32_e32 v44, 0x42, v138
	s_nop 0
	v_cndmask_b32_e32 v75, v217, v45, vcc
	v_cmp_le_u32_e32 vcc, v44, v43
	v_or_b32_e32 v44, 0x43, v138
	v_or_b32_e32 v45, 0x44, v138
	v_cndmask_b32_e32 v76, v217, v46, vcc
	v_cmp_le_u32_e32 vcc, v44, v43
	v_mov_b32_e32 v44, s22
	s_nop 0
	v_cndmask_b32_e32 v77, v217, v47, vcc
	s_waitcnt lgkmcnt(0)
	v_mfma_f32_16x16x32_bf16 v[46:49], v[92:95], v[24:27], v[48:51]
	v_cmp_gt_u32_e32 vcc, v45, v43
	s_nop 6
	v_cndmask_b32_e32 v78, v46, v44, vcc
	v_or_b32_e32 v44, 0x45, v138
	v_cmp_le_u32_e32 vcc, v44, v43
	v_or_b32_e32 v44, 0x46, v138
	s_nop 0
	v_cndmask_b32_e32 v79, v217, v47, vcc
	v_cmp_le_u32_e32 vcc, v44, v43
	v_or_b32_e32 v44, 0x47, v138
	s_nop 0
	v_cndmask_b32_e32 v80, v217, v48, vcc
	v_cmp_le_u32_e32 vcc, v44, v43
	s_nop 1
	v_cndmask_b32_e32 v81, v217, v49, vcc
	ds_read_b128 v[44:47], v248 offset:24576
	ds_read_b128 v[48:51], v248 offset:25600
	ds_read_b128 v[52:55], v249 offset:24576
	ds_read_b128 v[84:87], v249 offset:25600
	ds_read_b128 v[88:91], v250 offset:24576
	ds_read_b128 v[92:95], v250 offset:25600
	ds_read_b128 v[96:99], v220 offset:24576
	ds_read_b128 v[100:103], v220 offset:25600
	s_waitcnt lgkmcnt(7)
	v_mfma_f32_16x16x32_bf16 v[44:47], v[44:47], v[38:41], 0
	s_waitcnt lgkmcnt(5)
	v_mfma_f32_16x16x32_bf16 v[44:47], v[52:55], v[34:37], v[44:47]
	v_or_b32_e32 v53, 0x60, v138
	v_mov_b32_e32 v52, s22
	v_cmp_gt_u32_e32 vcc, v53, v43
	s_waitcnt lgkmcnt(3)
	v_mfma_f32_16x16x32_bf16 v[44:47], v[88:91], v[28:31], v[44:47]
	v_mfma_f32_16x16x32_bf16 v[48:51], v[48:51], v[38:41], 0
	s_waitcnt lgkmcnt(1)
	v_mfma_f32_16x16x32_bf16 v[44:47], v[96:99], v[24:27], v[44:47]
	v_mfma_f32_16x16x32_bf16 v[48:51], v[84:87], v[34:37], v[48:51]
	v_mfma_f32_16x16x32_bf16 v[48:51], v[92:95], v[28:31], v[48:51]
	s_nop 5
	v_cndmask_b32_e32 v82, v44, v52, vcc
	v_or_b32_e32 v44, 0x61, v138
	v_cmp_le_u32_e32 vcc, v44, v43
	v_or_b32_e32 v44, 0x62, v138
	s_nop 0
	v_cndmask_b32_e32 v83, v217, v45, vcc
	v_cmp_le_u32_e32 vcc, v44, v43
	v_or_b32_e32 v44, 0x63, v138
	v_or_b32_e32 v45, 0x64, v138
	v_cndmask_b32_e32 v84, v217, v46, vcc
	v_cmp_le_u32_e32 vcc, v44, v43
	v_mov_b32_e32 v44, s22
	s_nop 0
	v_cndmask_b32_e32 v85, v217, v47, vcc
	s_waitcnt lgkmcnt(0)
	v_mfma_f32_16x16x32_bf16 v[46:49], v[100:103], v[24:27], v[48:51]
	v_cmp_gt_u32_e32 vcc, v45, v43
	s_nop 6
	v_cndmask_b32_e32 v86, v46, v44, vcc
	v_or_b32_e32 v44, 0x65, v138
	v_cmp_le_u32_e32 vcc, v44, v43
	v_or_b32_e32 v44, 0x66, v138
	s_nop 0
	v_cndmask_b32_e32 v87, v217, v47, vcc
	v_cmp_le_u32_e32 vcc, v44, v43
	v_or_b32_e32 v44, 0x67, v138
	s_nop 0
	v_cndmask_b32_e32 v88, v217, v48, vcc
	v_cmp_le_u32_e32 vcc, v44, v43
	s_nop 1
	v_cndmask_b32_e32 v89, v217, v49, vcc
	ds_read_b128 v[44:47], v248 offset:32768
	ds_read_b128 v[48:51], v248 offset:33792
	ds_read_b128 v[52:55], v249 offset:32768
	ds_read_b128 v[92:95], v249 offset:33792
	ds_read_b128 v[96:99], v250 offset:32768
	ds_read_b128 v[100:103], v250 offset:33792
	ds_read_b128 v[114:117], v220 offset:32768
	ds_read_b128 v[118:121], v220 offset:33792
	s_waitcnt lgkmcnt(7)
	v_mfma_f32_16x16x32_bf16 v[44:47], v[44:47], v[38:41], 0
	s_waitcnt lgkmcnt(5)
	v_mfma_f32_16x16x32_bf16 v[44:47], v[52:55], v[34:37], v[44:47]
	v_or_b32_e32 v53, 0x80, v138
	v_mov_b32_e32 v52, s22
	v_cmp_gt_u32_e32 vcc, v53, v43
	s_waitcnt lgkmcnt(3)
	v_mfma_f32_16x16x32_bf16 v[44:47], v[96:99], v[28:31], v[44:47]
	v_mfma_f32_16x16x32_bf16 v[48:51], v[48:51], v[38:41], 0
	s_waitcnt lgkmcnt(1)
	v_mfma_f32_16x16x32_bf16 v[44:47], v[114:117], v[24:27], v[44:47]
	v_mfma_f32_16x16x32_bf16 v[48:51], v[92:95], v[34:37], v[48:51]
	v_mfma_f32_16x16x32_bf16 v[48:51], v[100:103], v[28:31], v[48:51]
	s_nop 5
	v_cndmask_b32_e32 v90, v44, v52, vcc
	v_or_b32_e32 v44, 0x81, v138
	v_cmp_le_u32_e32 vcc, v44, v43
	v_or_b32_e32 v44, 0x82, v138
	s_nop 0
	v_cndmask_b32_e32 v91, v217, v45, vcc
	v_cmp_le_u32_e32 vcc, v44, v43
	v_or_b32_e32 v44, 0x83, v138
	v_or_b32_e32 v45, 0x84, v138
	v_cndmask_b32_e32 v92, v217, v46, vcc
	v_cmp_le_u32_e32 vcc, v44, v43
	v_mov_b32_e32 v44, s22
	s_nop 0
	v_cndmask_b32_e32 v93, v217, v47, vcc
	s_waitcnt lgkmcnt(0)
	v_mfma_f32_16x16x32_bf16 v[46:49], v[118:121], v[24:27], v[48:51]
	v_cmp_gt_u32_e32 vcc, v45, v43
	s_nop 6
	v_cndmask_b32_e32 v94, v46, v44, vcc
	v_or_b32_e32 v44, 0x85, v138
	v_cmp_le_u32_e32 vcc, v44, v43
	v_or_b32_e32 v44, 0x86, v138
	s_nop 0
	v_cndmask_b32_e32 v95, v217, v47, vcc
	v_cmp_le_u32_e32 vcc, v44, v43
	v_or_b32_e32 v44, 0x87, v138
	s_nop 0
	v_cndmask_b32_e32 v96, v217, v48, vcc
	v_cmp_le_u32_e32 vcc, v44, v43
	s_nop 1
	v_cndmask_b32_e32 v97, v217, v49, vcc
	ds_read_b128 v[44:47], v248 offset:40960
	ds_read_b128 v[48:51], v248 offset:41984
	ds_read_b128 v[52:55], v249 offset:40960
	ds_read_b128 v[100:103], v249 offset:41984
	ds_read_b128 v[114:117], v250 offset:40960
	ds_read_b128 v[118:121], v250 offset:41984
	ds_read_b128 v[122:125], v220 offset:40960
	ds_read_b128 v[126:129], v220 offset:41984
	s_waitcnt lgkmcnt(7)
	v_mfma_f32_16x16x32_bf16 v[44:47], v[44:47], v[38:41], 0
	v_cmp_gt_u32_e32 vcc, v197, v43
	s_waitcnt lgkmcnt(5)
	v_mfma_f32_16x16x32_bf16 v[44:47], v[52:55], v[34:37], v[44:47]
	v_mov_b32_e32 v52, s22
	v_mfma_f32_16x16x32_bf16 v[48:51], v[48:51], v[38:41], 0
	s_waitcnt lgkmcnt(3)
	v_mfma_f32_16x16x32_bf16 v[44:47], v[114:117], v[28:31], v[44:47]
	v_mfma_f32_16x16x32_bf16 v[48:51], v[100:103], v[34:37], v[48:51]
	s_waitcnt lgkmcnt(1)
	v_mfma_f32_16x16x32_bf16 v[44:47], v[122:125], v[24:27], v[44:47]
	v_mfma_f32_16x16x32_bf16 v[48:51], v[118:121], v[28:31], v[48:51]
	s_nop 6
	v_cndmask_b32_e32 v98, v44, v52, vcc
	v_cmp_le_u32_e32 vcc, v199, v43
	v_mov_b32_e32 v44, s22
	s_nop 0
	v_cndmask_b32_e32 v99, v217, v45, vcc
	v_cmp_le_u32_e32 vcc, v201, v43
	s_nop 1
	v_cndmask_b32_e32 v102, v217, v46, vcc
	v_cmp_le_u32_e32 vcc, v202, v43
	s_nop 1
	v_cndmask_b32_e32 v103, v217, v47, vcc
	s_waitcnt lgkmcnt(0)
	v_mfma_f32_16x16x32_bf16 v[46:49], v[126:129], v[24:27], v[48:51]
	v_cmp_gt_u32_e32 vcc, v203, v43
	s_nop 6
	v_cndmask_b32_e32 v100, v46, v44, vcc
	v_cmp_le_u32_e32 vcc, v204, v43
	s_nop 1
	v_cndmask_b32_e32 v101, v217, v47, vcc
	v_cmp_le_u32_e32 vcc, v205, v43
	s_nop 1
	v_cndmask_b32_e32 v104, v217, v48, vcc
	v_cmp_le_u32_e32 vcc, v206, v43
	s_nop 1
	v_cndmask_b32_e32 v105, v217, v49, vcc
	ds_read_b128 v[44:47], v248 offset:49152
	ds_read_b128 v[48:51], v248 offset:50176
	ds_read_b128 v[52:55], v249 offset:49152
	ds_read_b128 v[114:117], v249 offset:50176
	ds_read_b128 v[118:121], v250 offset:49152
	ds_read_b128 v[122:125], v250 offset:50176
	ds_read_b128 v[126:129], v220 offset:49152
	ds_read_b128 v[130:133], v220 offset:50176
	s_waitcnt lgkmcnt(7)
	v_mfma_f32_16x16x32_bf16 v[44:47], v[44:47], v[38:41], 0
	v_cmp_gt_u32_e32 vcc, v207, v43
	s_waitcnt lgkmcnt(5)
	v_mfma_f32_16x16x32_bf16 v[44:47], v[52:55], v[34:37], v[44:47]
	v_mov_b32_e32 v52, s22
	v_mfma_f32_16x16x32_bf16 v[48:51], v[48:51], v[38:41], 0
	s_waitcnt lgkmcnt(3)
	v_mfma_f32_16x16x32_bf16 v[44:47], v[118:121], v[28:31], v[44:47]
	v_mfma_f32_16x16x32_bf16 v[48:51], v[114:117], v[34:37], v[48:51]
	s_waitcnt lgkmcnt(1)
	v_mfma_f32_16x16x32_bf16 v[44:47], v[126:129], v[24:27], v[44:47]
	v_mfma_f32_16x16x32_bf16 v[48:51], v[122:125], v[28:31], v[48:51]
	s_nop 6
	v_cndmask_b32_e32 v108, v44, v52, vcc
	v_cmp_le_u32_e32 vcc, v208, v43
	v_mov_b32_e32 v44, s22
	s_nop 0
	v_cndmask_b32_e32 v109, v217, v45, vcc
	v_cmp_le_u32_e32 vcc, v209, v43
	s_nop 1
	v_cndmask_b32_e32 v118, v217, v46, vcc
	v_cmp_le_u32_e32 vcc, v210, v43
	s_nop 1
	v_cndmask_b32_e32 v119, v217, v47, vcc
	s_waitcnt lgkmcnt(0)
	v_mfma_f32_16x16x32_bf16 v[46:49], v[130:133], v[24:27], v[48:51]
	v_cmp_gt_u32_e32 vcc, v211, v43
	s_nop 6
	v_cndmask_b32_e32 v116, v46, v44, vcc
	v_cmp_le_u32_e32 vcc, v212, v43
	s_nop 1
	v_cndmask_b32_e32 v117, v217, v47, vcc
	v_cmp_le_u32_e32 vcc, v213, v43
	s_nop 1
	v_cndmask_b32_e32 v120, v217, v48, vcc
	v_cmp_le_u32_e32 vcc, v221, v43
	s_nop 1
	v_cndmask_b32_e32 v121, v217, v49, vcc
	ds_read_b128 v[44:47], v248 offset:57344
	ds_read_b128 v[48:51], v248 offset:58368
	ds_read_b128 v[52:55], v249 offset:57344
	ds_read_b128 v[122:125], v249 offset:58368
	ds_read_b128 v[126:129], v250 offset:57344
	ds_read_b128 v[130:133], v250 offset:58368
	ds_read_b128 v[134:137], v220 offset:57344
	ds_read_b128 v[190:193], v220 offset:58368
	s_waitcnt lgkmcnt(7)
	v_mfma_f32_16x16x32_bf16 v[44:47], v[44:47], v[38:41], 0
	v_cmp_gt_u32_e32 vcc, v222, v43
	s_waitcnt lgkmcnt(5)
	v_mfma_f32_16x16x32_bf16 v[44:47], v[52:55], v[34:37], v[44:47]
	v_mfma_f32_16x16x32_bf16 v[48:51], v[48:51], v[38:41], 0
	v_mov_b32_e32 v38, s22
	s_waitcnt lgkmcnt(3)
	v_mfma_f32_16x16x32_bf16 v[44:47], v[126:129], v[28:31], v[44:47]
	v_mfma_f32_16x16x32_bf16 v[48:51], v[122:125], v[34:37], v[48:51]
	v_mov_b32_e32 v36, s22
	s_waitcnt lgkmcnt(1)
	v_mfma_f32_16x16x32_bf16 v[44:47], v[134:137], v[24:27], v[44:47]
	v_mfma_f32_16x16x32_bf16 v[28:31], v[130:133], v[28:31], v[48:51]
	s_waitcnt lgkmcnt(0)
	v_mfma_f32_16x16x32_bf16 v[24:27], v[190:193], v[24:27], v[28:31]
	s_nop 4
	v_cndmask_b32_e32 v38, v44, v38, vcc
	v_cmp_le_u32_e32 vcc, v223, v43
	s_nop 1
	v_cndmask_b32_e32 v39, v217, v45, vcc
	v_cmp_le_u32_e32 vcc, v224, v43
	s_nop 1
	v_cndmask_b32_e32 v34, v217, v46, vcc
	v_cmp_le_u32_e32 vcc, v225, v43
	s_nop 1
	v_cndmask_b32_e32 v35, v217, v47, vcc
	v_cmp_gt_u32_e32 vcc, v226, v43
	s_nop 1
	v_cndmask_b32_e32 v24, v24, v36, vcc
	v_cmp_le_u32_e32 vcc, v227, v43
	s_nop 1
	v_cndmask_b32_e32 v25, v217, v25, vcc
	v_cmp_le_u32_e32 vcc, v228, v43
	s_nop 1
	v_cndmask_b32_e32 v26, v217, v26, vcc
	v_cmp_le_u32_e32 vcc, v229, v43
	s_nop 1
	v_cndmask_b32_e32 v27, v217, v27, vcc
	v_max3_f32 v28, v42, v58, v59
	v_max3_f32 v29, v218, v60, v61
	v_and_b32_e32 v30, 64, v216
	v_max3_f32 v28, v28, v62, v63
	v_max3_f32 v29, v29, v64, v65
	v_add_u32_e32 v30, 64, v30
	v_max3_f32 v28, v28, v66, v67
	v_max3_f32 v29, v29, v68, v69
	ds_read_b128 v[42:45], v230
	ds_read_b128 v[46:49], v230 offset:8704
	ds_read_b128 v[50:53], v230 offset:17408
	ds_read_b128 v[54:57], v230 offset:26112
	v_max3_f32 v28, v28, v70, v71
	v_max3_f32 v29, v29, v72, v73
	s_nop 0
	v_max3_f32 v28, v28, v74, v75
	v_max3_f32 v29, v29, v76, v77
	s_nop 0
	v_max3_f32 v28, v28, v78, v79
	v_max3_f32 v29, v29, v80, v81
	s_nop 0
	v_max3_f32 v28, v28, v82, v83
	v_max3_f32 v29, v29, v84, v85
	s_nop 0
	v_max3_f32 v28, v28, v86, v87
	v_max3_f32 v29, v29, v88, v89
	s_nop 0
	v_max3_f32 v28, v28, v90, v91
	v_max3_f32 v29, v29, v92, v93
	s_nop 0
	v_max3_f32 v28, v28, v94, v95
	v_max3_f32 v29, v29, v96, v97
	s_nop 0
	v_max3_f32 v28, v28, v98, v99
	v_max3_f32 v29, v29, v102, v103
	s_nop 0
	v_max3_f32 v28, v28, v100, v101
	v_max3_f32 v29, v29, v104, v105
	s_nop 0
	v_max3_f32 v28, v28, v108, v109
	v_max3_f32 v29, v29, v118, v119
	s_nop 0
	v_max3_f32 v28, v28, v116, v117
	v_max3_f32 v29, v29, v120, v121
	s_nop 0
	v_max3_f32 v28, v28, v38, v39
	v_max3_f32 v29, v29, v34, v35
	s_nop 0
	v_max3_f32 v28, v28, v24, v25
	v_max3_f32 v29, v29, v26, v27
	s_nop 0
	v_max_f32 v28, v28, v29
	v_xor_b32_e32 v29, 16, v216
	v_cmp_lt_i32_e32 vcc, v29, v30
	s_nop 1
	v_cndmask_b32_e32 v29, v216, v29, vcc
	v_lshlrev_b32_e32 v160, 2, v29
	ds_bpermute_b32 v29, v160, v28
	s_waitcnt lgkmcnt(0)
	v_max_f32 v28, v28, v29
	v_xor_b32_e32 v29, 32, v216
	v_cmp_lt_i32_e32 vcc, v29, v30
	s_nop 1
	v_cndmask_b32_e32 v29, v216, v29, vcc
	v_lshlrev_b32_e32 v161, 2, v29
	ds_bpermute_b32 v29, v161, v28
	s_waitcnt lgkmcnt(0)
	v_max_f32 v114, v28, v29
	s_nop 0
	v_mov_b32_e32 v115, v114
	v_pk_add_f32 v[28:29], v[58:59], v[114:115] neg_lo:[0,1] neg_hi:[0,1]
	v_pk_add_f32 v[30:31], v[60:61], v[114:115] neg_lo:[0,1] neg_hi:[0,1]
	v_pk_add_f32 v[36:37], v[62:63], v[114:115] neg_lo:[0,1] neg_hi:[0,1]
	v_pk_add_f32 v[40:41], v[64:65], v[114:115] neg_lo:[0,1] neg_hi:[0,1]
	v_pk_add_f32 v[38:39], v[38:39], v[114:115] neg_lo:[0,1] neg_hi:[0,1]
	v_pk_add_f32 v[34:35], v[34:35], v[114:115] neg_lo:[0,1] neg_hi:[0,1]
	s_nop 0
	v_exp_f32_e32 v28, v28
	v_exp_f32_e32 v29, v29
	v_exp_f32_e32 v30, v30
	v_exp_f32_e32 v31, v31
	v_exp_f32_e32 v36, v36
	v_exp_f32_e32 v40, v40
	v_exp_f32_e32 v41, v41
	v_exp_f32_e32 v37, v37
	v_pk_add_f32 v[58:59], v[28:29], 0 op_sel_hi:[1,0]
	v_pk_add_f32 v[60:61], v[30:31], 0 op_sel_hi:[1,0]
	v_exp_f32_e32 v38, v38
	v_pk_add_f32 v[62:63], v[60:61], v[40:41]
	v_pk_add_f32 v[64:65], v[58:59], v[36:37]
	v_pk_add_f32 v[58:59], v[66:67], v[114:115] neg_lo:[0,1] neg_hi:[0,1]
	v_pk_add_f32 v[60:61], v[68:69], v[114:115] neg_lo:[0,1] neg_hi:[0,1]
	v_pk_add_f32 v[66:67], v[70:71], v[114:115] neg_lo:[0,1] neg_hi:[0,1]
	v_pk_add_f32 v[68:69], v[72:73], v[114:115] neg_lo:[0,1] neg_hi:[0,1]
	v_pk_add_f32 v[70:71], v[74:75], v[114:115] neg_lo:[0,1] neg_hi:[0,1]
	v_pk_add_f32 v[72:73], v[76:77], v[114:115] neg_lo:[0,1] neg_hi:[0,1]
	s_nop 0
	v_exp_f32_e32 v58, v58
	v_exp_f32_e32 v59, v59
	v_exp_f32_e32 v60, v60
	v_exp_f32_e32 v61, v61
	v_exp_f32_e32 v66, v66
	v_exp_f32_e32 v68, v68
	v_exp_f32_e32 v69, v69
	v_exp_f32_e32 v67, v67
	v_exp_f32_e32 v70, v70
	v_exp_f32_e32 v71, v71
	v_exp_f32_e32 v72, v72
	v_exp_f32_e32 v73, v73
	v_pk_add_f32 v[74:75], v[78:79], v[114:115] neg_lo:[0,1] neg_hi:[0,1]
	v_pk_add_f32 v[76:77], v[80:81], v[114:115] neg_lo:[0,1] neg_hi:[0,1]
	v_pk_add_f32 v[64:65], v[64:65], v[58:59]
	v_exp_f32_e32 v74, v74
	v_exp_f32_e32 v76, v76
	v_exp_f32_e32 v77, v77
	v_exp_f32_e32 v75, v75
	v_pk_add_f32 v[62:63], v[62:63], v[60:61]
	v_pk_add_f32 v[78:79], v[82:83], v[114:115] neg_lo:[0,1] neg_hi:[0,1]
	v_pk_add_f32 v[80:81], v[84:85], v[114:115] neg_lo:[0,1] neg_hi:[0,1]
	v_pk_add_f32 v[64:65], v[64:65], v[66:67]
	v_exp_f32_e32 v122, v78
	v_exp_f32_e32 v123, v79
	v_exp_f32_e32 v124, v80
	v_exp_f32_e32 v125, v81
	v_pk_add_f32 v[62:63], v[62:63], v[68:69]
	v_pk_add_f32 v[78:79], v[86:87], v[114:115] neg_lo:[0,1] neg_hi:[0,1]
	v_pk_add_f32 v[80:81], v[88:89], v[114:115] neg_lo:[0,1] neg_hi:[0,1]
	v_pk_add_f32 v[64:65], v[64:65], v[70:71]
	v_exp_f32_e32 v126, v78
	v_exp_f32_e32 v128, v80
	v_exp_f32_e32 v129, v81
	v_exp_f32_e32 v127, v79
	v_pk_add_f32 v[62:63], v[62:63], v[72:73]
	v_pk_add_f32 v[78:79], v[90:91], v[114:115] neg_lo:[0,1] neg_hi:[0,1]
	v_pk_add_f32 v[80:81], v[92:93], v[114:115] neg_lo:[0,1] neg_hi:[0,1]
	v_pk_add_f32 v[64:65], v[64:65], v[74:75]
	v_exp_f32_e32 v130, v78
	v_exp_f32_e32 v131, v79
	v_exp_f32_e32 v132, v80
	v_exp_f32_e32 v133, v81
	v_pk_add_f32 v[62:63], v[62:63], v[76:77]
	v_pk_add_f32 v[78:79], v[94:95], v[114:115] neg_lo:[0,1] neg_hi:[0,1]
	v_pk_add_f32 v[80:81], v[96:97], v[114:115] neg_lo:[0,1] neg_hi:[0,1]
	v_pk_add_f32 v[64:65], v[64:65], v[122:123]
	v_exp_f32_e32 v134, v78
	v_exp_f32_e32 v136, v80
	v_exp_f32_e32 v137, v81
	v_exp_f32_e32 v135, v79
	v_pk_add_f32 v[62:63], v[62:63], v[124:125]
	v_pk_add_f32 v[78:79], v[98:99], v[114:115] neg_lo:[0,1] neg_hi:[0,1]
	v_pk_add_f32 v[80:81], v[102:103], v[114:115] neg_lo:[0,1] neg_hi:[0,1]
	v_pk_add_f32 v[64:65], v[64:65], v[126:127]
	v_exp_f32_e32 v158, v78
	v_exp_f32_e32 v159, v79
	v_exp_f32_e32 v190, v80
	v_exp_f32_e32 v191, v81
	v_pk_add_f32 v[62:63], v[62:63], v[128:129]
	v_pk_add_f32 v[78:79], v[100:101], v[114:115] neg_lo:[0,1] neg_hi:[0,1]
	v_pk_add_f32 v[80:81], v[104:105], v[114:115] neg_lo:[0,1] neg_hi:[0,1]
	v_pk_add_f32 v[64:65], v[64:65], v[130:131]
	v_exp_f32_e32 v192, v78
	v_exp_f32_e32 v194, v80
	v_exp_f32_e32 v195, v81
	v_exp_f32_e32 v193, v79
	v_pk_add_f32 v[62:63], v[62:63], v[132:133]
	v_pk_add_f32 v[78:79], v[108:109], v[114:115] neg_lo:[0,1] neg_hi:[0,1]
	v_pk_add_f32 v[80:81], v[118:119], v[114:115] neg_lo:[0,1] neg_hi:[0,1]
	v_pk_add_f32 v[64:65], v[64:65], v[134:135]
	v_exp_f32_e32 v108, v78
	v_exp_f32_e32 v109, v79
	v_exp_f32_e32 v118, v80
	v_exp_f32_e32 v119, v81
	v_pk_add_f32 v[62:63], v[62:63], v[136:137]
	v_pk_add_f32 v[78:79], v[116:117], v[114:115] neg_lo:[0,1] neg_hi:[0,1]
	v_pk_add_f32 v[80:81], v[120:121], v[114:115] neg_lo:[0,1] neg_hi:[0,1]
	v_pk_add_f32 v[64:65], v[64:65], v[158:159]
	v_exp_f32_e32 v116, v78
	v_exp_f32_e32 v120, v80
	v_exp_f32_e32 v121, v81
	v_exp_f32_e32 v117, v79
	v_pk_add_f32 v[62:63], v[62:63], v[190:191]
	v_exp_f32_e32 v39, v39
	v_exp_f32_e32 v34, v34
	v_exp_f32_e32 v35, v35
	v_pk_add_f32 v[24:25], v[24:25], v[114:115] neg_lo:[0,1] neg_hi:[0,1]
	v_pk_add_f32 v[26:27], v[26:27], v[114:115] neg_lo:[0,1] neg_hi:[0,1]
	v_pk_add_f32 v[62:63], v[62:63], v[194:195]
	v_pk_add_f32 v[64:65], v[64:65], v[192:193]
	v_exp_f32_e32 v24, v24
	v_exp_f32_e32 v26, v26
	v_exp_f32_e32 v27, v27
	v_exp_f32_e32 v25, v25
	v_pk_add_f32 v[64:65], v[64:65], v[108:109]
	v_pk_add_f32 v[62:63], v[62:63], v[118:119]
	v_pk_add_f32 v[64:65], v[64:65], v[116:117]
	v_pk_add_f32 v[62:63], v[62:63], v[120:121]
	v_pk_add_f32 v[64:65], v[64:65], v[38:39]
	v_pk_add_f32 v[62:63], v[62:63], v[34:35]
	v_pk_add_f32 v[64:65], v[64:65], v[24:25]
	v_pk_add_f32 v[62:63], v[62:63], v[26:27]
	v_add_f32_e32 v64, v64, v65
	v_add_f32_e32 v62, v62, v63
	v_add_f32_e32 v62, v64, v62
	ds_bpermute_b32 v63, v160, v62
	ds_read_b128 v[90:93], v230 offset:34816
	ds_read_b128 v[94:97], v230 offset:43520
	ds_read_b128 v[98:101], v230 offset:52224
	ds_read_b128 v[86:89], v230 offset:60928
	v_cvt_pk_bf16_f32 v102, v28, v29
	v_cvt_pk_bf16_f32 v103, v30, v31
	v_cvt_pk_bf16_f32 v104, v36, v37
	s_waitcnt lgkmcnt(4)
	v_add_f32_e32 v185, v62, v63
	ds_bpermute_b32 v187, v161, v185
	v_cvt_pk_bf16_f32 v105, v40, v41
	v_cvt_pk_bf16_f32 v82, v58, v59
	v_cvt_pk_bf16_f32 v83, v60, v61
	v_cvt_pk_bf16_f32 v84, v66, v67
	v_cvt_pk_bf16_f32 v85, v68, v69
	v_cvt_pk_bf16_f32 v78, v70, v71
	v_cvt_pk_bf16_f32 v79, v72, v73
	v_cvt_pk_bf16_f32 v80, v74, v75
	v_cvt_pk_bf16_f32 v81, v76, v77
	v_cvt_pk_bf16_f32 v74, v122, v123
	v_cvt_pk_bf16_f32 v75, v124, v125
	v_cvt_pk_bf16_f32 v76, v126, v127
	v_cvt_pk_bf16_f32 v77, v128, v129
	v_cvt_pk_bf16_f32 v70, v130, v131
	v_cvt_pk_bf16_f32 v71, v132, v133
	v_cvt_pk_bf16_f32 v72, v134, v135
	v_cvt_pk_bf16_f32 v73, v136, v137
	v_cvt_pk_bf16_f32 v66, v158, v159
	v_cvt_pk_bf16_f32 v67, v190, v191
	v_cvt_pk_bf16_f32 v68, v192, v193
	v_cvt_pk_bf16_f32 v69, v194, v195
	v_cvt_pk_bf16_f32 v62, v108, v109
	v_cvt_pk_bf16_f32 v63, v118, v119
	v_cvt_pk_bf16_f32 v64, v116, v117
	v_cvt_pk_bf16_f32 v65, v120, v121
	v_cvt_pk_bf16_f32 v58, v38, v39
	v_cvt_pk_bf16_f32 v59, v34, v35
	v_cvt_pk_bf16_f32 v60, v24, v25
	v_cvt_pk_bf16_f32 v61, v26, v27
	s_add_i32 s28, s23, 8
	s_cmp_lg_u32 s23, 24
	s_cselect_b32 s23, s28, 24
	s_add_i32 s23, s23, s11
	s_lshl_b32 s29, s23, 4
	s_and_b32 s29, s29, 0xf0
	v_or_b32_e32 v108, s29, v183
	s_ashr_i32 s23, s23, 4
	v_ashrrev_i32_e32 v109, 31, v108
	s_add_i32 s23, s23, s19
	v_lshlrev_b64 v[24:25], 11, v[108:109]
	s_lshl_b32 s30, s23, 7
	v_lshl_add_u64 v[24:25], s[0:1], 0, v[24:25]
	s_ashr_i32 s31, s30, 31
	v_lshl_add_u64 v[24:25], s[30:31], 1, v[24:25]
	v_lshl_add_u64 v[24:25], v[24:25], 0, v[32:33]
	global_load_dwordx4 v[38:41], v[24:25], off
	global_load_dwordx4 v[34:37], v[24:25], off offset:64
	global_load_dwordx4 v[28:31], v[24:25], off offset:128
	s_nop 0
	global_load_dwordx4 v[24:27], v[24:25], off offset:192
	s_ashr_i32 s29, s23, 31
	v_mov_b32_e32 v116, s23
	v_mov_b32_e32 v117, s29
	s_and_b64 vcc, exec, s[38:39]
	v_lshl_add_u64 v[108:109], v[108:109], 3, v[116:117]
	s_cbranch_vccnz .LBB0_1128
	v_mad_u64_u32 v[116:117], s[30:31], v108, 24, s[4:5]
	v_mad_i32_i24 v117, v109, 24, v117
	global_load_dwordx2 v[190:191], v[116:117], off
	s_branch .LBB0_1129

.LBB0_1133:
	s_waitcnt vmcnt(7)
	v_sub_f32_e32 v106, v106, v114
	v_exp_f32_e32 v106, v106
	s_and_b64 vcc, exec, s[38:39]
	v_mul_f32_e32 v196, v107, v106
	s_cbranch_vccnz .LBB0_1135
	v_cvt_pk_f32_fp8_sdwa v[106:107], v20 src0_sel:WORD_1
	v_cvt_pk_f32_fp8_e32 v[116:117], v20
	v_pk_fma_f32 v[108:109], v[196:197], v[106:107], 0 op_sel_hi:[0,1,0]
	v_pk_fma_f32 v[106:107], v[196:197], v[116:117], 0 op_sel_hi:[0,1,0]
	s_branch .LBB0_1136
